# FFN-in weights stored k-blocked by PREP ([K/32][N][32]: each LDS-DMA weight piece = one contiguous KiB, 8 full cache lines instead of 16 half lines); FFN1 B-operand addressing follows
# speedup vs baseline: 1.0187x; 1.0185x over previous
.LBB0_166:
	s_ashr_i32 s5, s4, 31
	s_lshr_b32 s5, s5, 28
	s_add_i32 s5, s4, s5
	s_ashr_i32 s14, s5, 4
	s_and_b32 s5, s5, -16
	s_sub_i32 s46, s4, s5
	v_readlane_b32 s4, v254, 52
	s_waitcnt vmcnt(6)
	v_mov_b32_e32 v58, v224
	s_add_i32 s46, s46, s4
	s_lshl_b32 s97, s14, 8
	v_readfirstlane_b32 s4, v58
	v_bfe_u32 v59, v58, 4, 2
	s_and_b32 s13, s4, 0xffffffc0
	s_waitcnt vmcnt(4)
	v_bfe_u32 v42, v58, 2, 4
	v_sub_u32_e32 v60, 0, v59
	s_add_i32 s13, s13, s97
	v_xor_b32_e32 v0, v58, v60
	v_or_b32_e32 v6, s13, v42
	v_lshlrev_b32_e32 v0, 4, v0
	v_min_i32_e32 v4, 0x157f, v6
	v_and_b32_e32 v0, 48, v0
	v_ashrrev_i32_e32 v5, 31, v4
	v_lshl_add_u64 v[2:3], s[74:75], 0, v[0:1]
	v_lshlrev_b64 v[4:5], 6, v[4:5]
	v_lshl_add_u64 v[34:35], v[2:3], 0, v[4:5]
	v_or_b32_e32 v4, 16, v6
	v_min_i32_e32 v4, 0x157f, v4
	v_ashrrev_i32_e32 v5, 31, v4
	v_lshlrev_b64 v[4:5], 6, v[4:5]
	v_lshl_add_u64 v[36:37], v[2:3], 0, v[4:5]
	v_or_b32_e32 v4, 32, v6
	v_min_i32_e32 v4, 0x157f, v4
	s_ashr_i32 s5, s4, 6
	v_ashrrev_i32_e32 v5, 31, v4
	s_and_b32 s12, s5, 1
	v_lshlrev_b64 v[4:5], 6, v[4:5]
	s_lshl_b32 s15, s46, 7
	v_lshl_add_u64 v[38:39], v[2:3], 0, v[4:5]
	v_or_b32_e32 v4, 48, v6
	s_lshl_b32 s13, s12, 6
	v_min_i32_e32 v4, 0x157f, v4
	v_and_b32_e32 v61, 15, v58
	s_or_b32 s13, s13, s15
	v_ashrrev_i32_e32 v5, 31, v4
	s_waitcnt vmcnt(1)
	v_or_b32_e32 v14, s13, v61
	v_lshlrev_b64 v[4:5], 6, v[4:5]
	v_ashrrev_i32_e32 v15, 31, v14
	v_lshl_add_u64 v[40:41], v[2:3], 0, v[4:5]
	v_lshlrev_b64 v[2:3], 5, v[14:15]
	v_lshl_add_u64 v[2:3], s[70:71], 0, v[2:3]
	s_waitcnt vmcnt(0)
	s_waitcnt lgkmcnt(0)
	s_barrier
	global_load_dwordx4 v[6:9], v[2:3], off offset:16
	global_load_dwordx4 v[22:25], v[2:3], off
	v_or_b32_e32 v2, 16, v14
	v_ashrrev_i32_e32 v3, 31, v2
	v_lshlrev_b64 v[2:3], 5, v[2:3]
	v_lshl_add_u64 v[10:11], s[70:71], 0, v[2:3]
	global_load_dwordx4 v[2:5], v[10:11], off offset:16
	global_load_dwordx4 v[18:21], v[10:11], off
	v_or_b32_e32 v10, 32, v14
	v_or_b32_e32 v14, 48, v14
	v_ashrrev_i32_e32 v11, 31, v10
	v_ashrrev_i32_e32 v15, 31, v14
	v_lshlrev_b64 v[10:11], 5, v[10:11]
	v_lshlrev_b64 v[14:15], 5, v[14:15]
	v_lshl_add_u64 v[16:17], s[70:71], 0, v[10:11]
	v_lshl_add_u64 v[30:31], s[70:71], 0, v[14:15]
	global_load_dwordx4 v[10:13], v[16:17], off offset:16
	global_load_dwordx4 v[26:29], v[16:17], off
	s_nop 0
	global_load_dwordx4 v[14:17], v[30:31], off offset:16
	s_nop 0
	global_load_dwordx4 v[30:33], v[30:31], off
	s_lshl_b32 s13, s5, 1
	s_waitcnt vmcnt(8)
	v_or_b32_e32 v46, s15, v42
	v_lshl_add_u32 v44, s5, 5, v46
	s_lshl_b32 s40, s13, 10
	s_or_b32 s13, s13, 1
	v_ashrrev_i32_e32 v45, 31, v44
	v_lshl_add_u32 v46, s13, 4, v46
	v_lshl_add_u64 v[42:43], s[2:3], 0, v[0:1]
	v_lshlrev_b64 v[162:163], 10, v[44:45]
	v_lshlrev_b64 v[44:45], 11, v[44:45]
	v_ashrrev_i32_e32 v47, 31, v46
	v_lshl_add_u64 v[44:45], v[42:43], 0, v[44:45]
	v_lshlrev_b64 v[164:165], 10, v[46:47]
	v_lshlrev_b64 v[46:47], 11, v[46:47]
	s_mov_b32 s41, m0
	s_mov_b32 m0, s40
	s_nop 0
	global_load_lds_dwordx4 v[44:45], off
	s_mov_b32 m0, s41
	v_lshl_add_u64 v[42:43], v[42:43], 0, v[46:47]
	s_lshl_b32 s42, s5, 12
	s_add_i32 s43, s40, 0x6000
	s_lshl_b32 s40, s13, 10
	s_mov_b32 s13, m0
	s_mov_b32 m0, s40
	s_nop 0
	global_load_lds_dwordx4 v[42:43], off
	s_mov_b32 m0, s13
	s_add_i32 s41, s42, 0x2000
	s_mov_b32 s13, m0
	s_mov_b32 m0, s41
	s_nop 0
	global_load_lds_dwordx4 v[34:35], off
	s_mov_b32 m0, s13
	s_add_i32 s13, s42, 0x2400
	s_mov_b32 s44, m0
	s_mov_b32 m0, s13
	s_nop 0
	global_load_lds_dwordx4 v[36:37], off
	s_mov_b32 m0, s44
	s_add_i32 s13, s42, 0x2800
	s_mov_b32 s44, m0
	s_mov_b32 m0, s13
	s_nop 0
	global_load_lds_dwordx4 v[38:39], off
	s_mov_b32 m0, s44
	s_add_i32 s13, s42, 0x2c00
	s_mov_b32 s44, m0
	s_mov_b32 m0, s13
	s_nop 0
	global_load_lds_dwordx4 v[40:41], off
	s_mov_b32 m0, s44
	v_lshl_add_u64 v[46:47], v[44:45], 0, 64
	s_mov_b32 s13, m0
	s_mov_b32 m0, s43
	s_nop 0
	global_load_lds_dwordx4 v[46:47], off
	s_mov_b32 m0, s13
	v_lshl_add_u64 v[48:49], v[42:43], 0, 64
	s_add_i32 s13, s40, 0x6000
	s_mov_b32 s43, m0
	s_mov_b32 m0, s13
	s_nop 0
	global_load_lds_dwordx4 v[48:49], off
	s_mov_b32 m0, s43
	v_lshrrev_b32_e32 v0, 2, v58
	s_waitcnt vmcnt(25)
	s_mov_b32 s100, 0x56000
	s_mov_b32 s101, 0
	v_lshl_add_u64 v[50:51], v[34:35], 0, s[100:101]
	s_add_i32 s13, s42, 0x8000
	s_mov_b32 s43, m0
	s_mov_b32 m0, s13
	s_nop 0
	global_load_lds_dwordx4 v[50:51], off
	s_mov_b32 m0, s43
	v_sub_u32_e32 v0, 0, v0
	v_lshl_add_u64 v[52:53], v[36:37], 0, s[100:101]
	s_add_i32 s13, s42, 0x8400
	s_mov_b32 s43, m0
	s_mov_b32 m0, s13
	s_nop 0
	global_load_lds_dwordx4 v[52:53], off
	s_mov_b32 m0, s43
	v_bitop3_b32 v0, v59, v0, 3 bitop3:0x78
	s_and_b32 s4, s4, 0x3ffff80
	v_lshl_add_u64 v[54:55], v[38:39], 0, s[100:101]
	s_add_i32 s13, s42, 0x8800
	s_mov_b32 s43, m0
	s_mov_b32 m0, s13
	s_nop 0
	global_load_lds_dwordx4 v[54:55], off
	s_mov_b32 m0, s43
	v_lshlrev_b32_e32 v176, 4, v0
	v_or_b32_e32 v0, s4, v61
	v_lshl_add_u64 v[56:57], v[40:41], 0, s[100:101]
	s_add_i32 s42, s42, 0x8c00
	s_mov_b32 s13, m0
	s_mov_b32 m0, s42
	s_nop 0
	global_load_lds_dwordx4 v[56:57], off
	s_mov_b32 m0, s13
	v_lshlrev_b32_e32 v178, 6, v0
	v_bitop3_b32 v0, v58, 3, v60 bitop3:0x48
	s_mov_b32 s100, 0xac000
	v_lshl_add_u64 v[172:173], v[34:35], 0, s[100:101]
	v_lshlrev_b32_e32 v0, 4, v0
	v_mov_b32_e32 v34, 0
	v_mov_b32_e32 v221, 0x7f800000
	s_lshl_b32 s47, s12, 12
	v_lshlrev_b32_e32 v177, 6, v61
	s_lshl_b32 s42, s5, 11
	v_lshl_add_u64 v[166:167], v[40:41], 0, s[100:101]
	v_lshl_add_u64 v[168:169], v[38:39], 0, s[100:101]
	v_lshl_add_u64 v[170:171], v[36:37], 0, s[100:101]
	v_lshl_add_u64 v[174:175], s[0:1], 0, v[0:1]
	s_mov_b64 s[12:13], 0
	s_mov_b32 s43, 0
	v_mov_b32_e32 v35, v34
	v_mov_b32_e32 v36, v34
	v_mov_b32_e32 v37, v34
	v_mov_b32_e32 v38, v34
	v_mov_b32_e32 v39, v34
	v_mov_b32_e32 v40, v34
	v_mov_b32_e32 v41, v34
	v_mov_b32_e32 v42, v34
	v_mov_b32_e32 v43, v34
	v_mov_b32_e32 v44, v34
	v_mov_b32_e32 v45, v34
	v_mov_b32_e32 v46, v34
	v_mov_b32_e32 v47, v34
	v_mov_b32_e32 v48, v34
	v_mov_b32_e32 v49, v34
	v_mov_b32_e32 v50, v34
	v_mov_b32_e32 v51, v34
	v_mov_b32_e32 v52, v34
	v_mov_b32_e32 v53, v34
	v_mov_b32_e32 v54, v34
	v_mov_b32_e32 v55, v34
	v_mov_b32_e32 v56, v34
	v_mov_b32_e32 v57, v34
	v_mov_b32_e32 v58, v34
	v_mov_b32_e32 v59, v34
	v_mov_b32_e32 v60, v34
	v_mov_b32_e32 v61, v34
	s_waitcnt vmcnt(24)
	v_mov_b32_e32 v62, v34
	v_mov_b32_e32 v63, v34
	v_mov_b32_e32 v64, v34
	v_mov_b32_e32 v65, v34
	v_mov_b32_e32 v66, v34
	v_mov_b32_e32 v67, v34
	v_mov_b32_e32 v68, v34
	v_mov_b32_e32 v69, v34
	v_mov_b32_e32 v70, v34
	v_mov_b32_e32 v71, v34
	v_mov_b32_e32 v72, v34
	v_mov_b32_e32 v73, v34
	v_mov_b32_e32 v74, v34
	v_mov_b32_e32 v75, v34
	v_mov_b32_e32 v76, v34
	v_mov_b32_e32 v77, v34
	v_mov_b32_e32 v78, v34
	v_mov_b32_e32 v79, v34
	v_mov_b32_e32 v80, v34
	v_mov_b32_e32 v81, v34
	v_mov_b32_e32 v82, v34
	v_mov_b32_e32 v83, v34
	v_mov_b32_e32 v84, v34
	v_mov_b32_e32 v85, v34
	v_mov_b32_e32 v86, v34
	v_mov_b32_e32 v87, v34
	v_mov_b32_e32 v88, v34
	v_mov_b32_e32 v89, v34
	v_mov_b32_e32 v90, v34
	v_mov_b32_e32 v91, v34
	v_mov_b32_e32 v92, v34
	v_mov_b32_e32 v93, v34
	v_mov_b32_e32 v94, v34
	v_mov_b32_e32 v95, v34
	v_mov_b32_e32 v96, v34
	v_mov_b32_e32 v97, v34
	v_mov_b32_e32 v98, v34
	v_mov_b32_e32 v99, v34
	v_mov_b32_e32 v100, v34
	v_mov_b32_e32 v101, v34
	v_mov_b32_e32 v102, v34
	v_mov_b32_e32 v103, v34
	v_mov_b32_e32 v104, v34
	v_mov_b32_e32 v105, v34
	v_mov_b32_e32 v106, v34
	v_mov_b32_e32 v107, v34
	v_mov_b32_e32 v108, v34
	v_mov_b32_e32 v109, v34
	v_mov_b32_e32 v110, v34
	v_mov_b32_e32 v111, v34
	v_mov_b32_e32 v112, v34
	v_mov_b32_e32 v113, v34
	v_mov_b32_e32 v114, v34
	v_mov_b32_e32 v115, v34
	v_mov_b32_e32 v116, v34
	v_mov_b32_e32 v117, v34
	v_mov_b32_e32 v118, v34
	v_mov_b32_e32 v119, v34
	v_mov_b32_e32 v120, v34
	v_mov_b32_e32 v121, v34
	v_mov_b32_e32 v122, v34
	v_mov_b32_e32 v123, v34
	v_mov_b32_e32 v124, v34
	v_mov_b32_e32 v125, v34
	v_mov_b32_e32 v126, v34
	v_mov_b32_e32 v127, v34
	v_mov_b32_e32 v128, v34
	v_mov_b32_e32 v129, v34
	v_mov_b32_e32 v130, v34
	v_mov_b32_e32 v131, v34
	v_mov_b32_e32 v132, v34
	v_mov_b32_e32 v133, v34
	v_mov_b32_e32 v134, v34
	v_mov_b32_e32 v135, v34
	v_mov_b32_e32 v136, v34
	v_mov_b32_e32 v137, v34
	v_mov_b32_e32 v138, v34
	v_mov_b32_e32 v139, v34
	v_mov_b32_e32 v140, v34
	v_mov_b32_e32 v141, v34
	v_mov_b32_e32 v142, v34
	v_mov_b32_e32 v143, v34
	v_mov_b32_e32 v144, v34
	v_mov_b32_e32 v145, v34
	v_mov_b32_e32 v146, v34
	v_mov_b32_e32 v147, v34
	v_mov_b32_e32 v148, v34
	v_mov_b32_e32 v149, v34
	v_mov_b32_e32 v150, v34
	v_mov_b32_e32 v151, v34
	v_mov_b32_e32 v152, v34
	v_mov_b32_e32 v153, v34
	v_mov_b32_e32 v154, v34
	v_mov_b32_e32 v155, v34
	v_mov_b32_e32 v156, v34
	v_mov_b32_e32 v157, v34
	v_mov_b32_e32 v158, v34
	v_mov_b32_e32 v159, v34
	v_mov_b32_e32 v160, v34
	v_mov_b32_e32 v161, v34
.LBB0_167:
	s_mul_i32 s100, s12, 0x1580
	s_mul_i32 s4, s43, 0x6000
	s_add_i32 s5, s4, 0xffffa000
	s_cmp_gt_i32 s43, 0
	s_waitcnt vmcnt(6)
	s_cselect_b32 s5, s5, 0xc000
	s_waitcnt lgkmcnt(0)
	s_barrier
	s_setprio 2
	v_add3_u32 v0, s4, v177, v176
	v_add_u32_e32 v0, s47, v0
	v_add3_u32 v212, s4, v178, v176
	ds_read_b128 v[196:199], v212 offset:8192
	ds_read_b128 v[180:183], v0
	ds_read_b128 v[184:187], v0 offset:1024
	ds_read_b128 v[188:191], v0 offset:2048
	ds_read_b128 v[192:195], v0 offset:3072
	ds_read_b128 v[200:203], v212 offset:9216
	ds_read_b128 v[204:207], v212 offset:10240
	ds_read_b128 v[208:211], v212 offset:11264
	ds_read_b128 v[216:219], v212 offset:12288
	ds_read_b128 v[226:229], v212 offset:13312
	ds_read_b128 v[230:233], v212 offset:14336
	ds_read_b128 v[234:237], v212 offset:15360
	v_lshl_add_u64 v[212:213], v[174:175], 0, s[12:13]
	v_lshl_add_u64 v[212:213], v[162:163], 1, v[212:213]
	s_add_i32 s44, s5, s42
	s_mov_b32 m0, s44
	s_nop 0
	global_load_lds_dwordx4 v[212:213], off
	v_lshl_add_u64 v[212:213], v[174:175], 0, s[12:13]
	v_lshl_add_u64 v[212:213], v[164:165], 1, v[212:213]
	s_add_i32 s44, s5, s40
	s_mov_b32 m0, s44
	s_nop 0
	global_load_lds_dwordx4 v[212:213], off
	s_add_i32 s5, s41, s5
	v_lshl_add_u64 v[212:213], v[172:173], 0, s[100:101]
	s_mov_b32 m0, s5
	s_nop 0
	global_load_lds_dwordx4 v[212:213], off
	v_lshl_add_u64 v[212:213], v[170:171], 0, s[100:101]
	s_add_i32 s44, s5, 0x400
	s_mov_b32 m0, s44
	s_nop 0
	global_load_lds_dwordx4 v[212:213], off
	v_lshl_add_u64 v[212:213], v[168:169], 0, s[100:101]
	s_add_i32 s44, s5, 0x800
	s_mov_b32 m0, s44
	s_nop 0
	global_load_lds_dwordx4 v[212:213], off
	s_addk_i32 s5, 0xc00
	v_lshl_add_u64 v[212:213], v[166:167], 0, s[100:101]
	s_mov_b32 m0, s5
	s_nop 0
	global_load_lds_dwordx4 v[212:213], off
	s_setprio 0
	s_waitcnt lgkmcnt(10)
	v_mfma_f32_16x16x32_bf16 v[34:37], v[196:199], v[180:183], v[34:37]
	s_waitcnt lgkmcnt(9)
	v_mfma_f32_16x16x32_bf16 v[38:41], v[196:199], v[184:187], v[38:41]
	s_waitcnt lgkmcnt(8)
	v_mfma_f32_16x16x32_bf16 v[42:45], v[196:199], v[188:191], v[42:45]
	s_waitcnt lgkmcnt(7)
	v_mfma_f32_16x16x32_bf16 v[46:49], v[196:199], v[192:195], v[46:49]
	s_waitcnt lgkmcnt(6)
	v_mfma_f32_16x16x32_bf16 v[50:53], v[200:203], v[180:183], v[50:53]
	v_mfma_f32_16x16x32_bf16 v[54:57], v[200:203], v[184:187], v[54:57]
	v_mfma_f32_16x16x32_bf16 v[58:61], v[200:203], v[188:191], v[58:61]
	v_mfma_f32_16x16x32_bf16 v[62:65], v[200:203], v[192:195], v[62:65]
	s_waitcnt lgkmcnt(5)
	v_mfma_f32_16x16x32_bf16 v[66:69], v[204:207], v[180:183], v[66:69]
	v_mfma_f32_16x16x32_bf16 v[70:73], v[204:207], v[184:187], v[70:73]
	v_mfma_f32_16x16x32_bf16 v[74:77], v[204:207], v[188:191], v[74:77]
	v_mfma_f32_16x16x32_bf16 v[78:81], v[204:207], v[192:195], v[78:81]
	s_waitcnt lgkmcnt(4)
	v_mfma_f32_16x16x32_bf16 v[82:85], v[208:211], v[180:183], v[82:85]
	v_mfma_f32_16x16x32_bf16 v[86:89], v[208:211], v[184:187], v[86:89]
	v_mfma_f32_16x16x32_bf16 v[90:93], v[208:211], v[188:191], v[90:93]
	v_mfma_f32_16x16x32_bf16 v[94:97], v[208:211], v[192:195], v[94:97]
	s_waitcnt lgkmcnt(3)
	v_mfma_f32_16x16x32_bf16 v[98:101], v[216:219], v[180:183], v[98:101]
	v_mfma_f32_16x16x32_bf16 v[102:105], v[216:219], v[184:187], v[102:105]
	v_mfma_f32_16x16x32_bf16 v[106:109], v[216:219], v[188:191], v[106:109]
	v_mfma_f32_16x16x32_bf16 v[110:113], v[216:219], v[192:195], v[110:113]
	s_waitcnt lgkmcnt(2)
	v_mfma_f32_16x16x32_bf16 v[114:117], v[226:229], v[180:183], v[114:117]
	v_mfma_f32_16x16x32_bf16 v[118:121], v[226:229], v[184:187], v[118:121]
	v_mfma_f32_16x16x32_bf16 v[122:125], v[226:229], v[188:191], v[122:125]
	v_mfma_f32_16x16x32_bf16 v[126:129], v[226:229], v[192:195], v[126:129]
	s_waitcnt lgkmcnt(1)
	v_mfma_f32_16x16x32_bf16 v[130:133], v[230:233], v[180:183], v[130:133]
	v_mfma_f32_16x16x32_bf16 v[134:137], v[230:233], v[184:187], v[134:137]
	v_mfma_f32_16x16x32_bf16 v[138:141], v[230:233], v[188:191], v[138:141]
	v_mfma_f32_16x16x32_bf16 v[142:145], v[230:233], v[192:195], v[142:145]
	s_waitcnt lgkmcnt(0)
	v_mfma_f32_16x16x32_bf16 v[146:149], v[234:237], v[180:183], v[146:149]
	v_mfma_f32_16x16x32_bf16 v[150:153], v[234:237], v[184:187], v[150:153]
	v_mfma_f32_16x16x32_bf16 v[154:157], v[234:237], v[188:191], v[154:157]
	v_mfma_f32_16x16x32_bf16 v[158:161], v[234:237], v[192:195], v[158:161]
	s_add_i32 s4, s43, 1
	s_cmp_lg_u32 s43, 2
	s_cselect_b32 s43, s4, 0
	s_add_u32 s12, s12, 64
	s_addc_u32 s13, s13, 0
	s_cmpk_eq_i32 s12, 0x780
	s_cbranch_scc0 .LBB0_167
	s_waitcnt vmcnt(6)
	v_mov_b32_e32 v162, v23
	v_mov_b32_e32 v163, v24
	v_mov_b32_e32 v23, v25
	v_mov_b32_e32 v164, v7
	v_mov_b32_e32 v165, v8
	v_pk_add_f32 v[22:23], v[162:163], v[22:23]
	v_mov_b32_e32 v7, v9
	v_pk_add_f32 v[6:7], v[164:165], v[6:7]
	v_add_f32_e32 v0, v22, v23
	v_add_f32_e32 v0, v0, v6
	v_add_f32_e32 v0, v0, v7
	v_fmamk_f32 v0, v0, 0x3a800000, v250
	s_mov_b32 s4, 0x800000
	s_waitcnt vmcnt(4)
	v_mov_b32_e32 v166, v19
	v_mov_b32_e32 v167, v20
	v_mov_b32_e32 v168, v3
	v_mul_f32_e32 v3, 0x4b800000, v0
	v_cmp_gt_f32_e32 vcc, s4, v0
	v_mov_b32_e32 v19, v21
	v_mov_b32_e32 v169, v4
	v_cndmask_b32_e32 v0, v0, v3, vcc
	v_pk_add_f32 v[6:7], v[166:167], v[18:19]
	v_mov_b32_e32 v3, v5
	v_pk_add_f32 v[2:3], v[168:169], v[2:3]
	v_add_f32_e32 v4, v6, v7
	v_add_f32_e32 v2, v4, v2
	v_add_f32_e32 v2, v2, v3
	v_fmamk_f32 v2, v2, 0x3a800000, v250
	v_mul_f32_e32 v3, 0x4b800000, v2
	v_cmp_gt_f32_e64 s[40:41], s4, v2
	s_waitcnt vmcnt(2)
	v_mov_b32_e32 v170, v27
	v_mov_b32_e32 v171, v28
	v_cndmask_b32_e64 v2, v2, v3, s[40:41]
	v_mov_b32_e32 v27, v29
	v_mov_b32_e32 v172, v11
	v_mov_b32_e32 v173, v12
	v_rsq_f32_e32 v182, v2
	v_pk_add_f32 v[2:3], v[170:171], v[26:27]
	v_mov_b32_e32 v11, v13
	v_pk_add_f32 v[4:5], v[172:173], v[10:11]
	v_add_f32_e32 v2, v2, v3
	v_add_f32_e32 v2, v2, v4
	v_add_f32_e32 v2, v2, v5
	v_fmamk_f32 v2, v2, 0x3a800000, v250
	v_mul_f32_e32 v3, 0x4b800000, v2
	v_cmp_gt_f32_e64 s[42:43], s4, v2
	s_waitcnt vmcnt(0)
	v_mov_b32_e32 v174, v31
	v_mov_b32_e32 v175, v32
	v_cndmask_b32_e64 v2, v2, v3, s[42:43]
	v_mov_b32_e32 v31, v33
	v_mov_b32_e32 v180, v15
	v_mov_b32_e32 v181, v16
	v_rsq_f32_e32 v183, v2
	v_pk_add_f32 v[2:3], v[174:175], v[30:31]
	v_mov_b32_e32 v15, v17
	v_pk_add_f32 v[4:5], v[180:181], v[14:15]
	v_add_f32_e32 v2, v2, v3
	v_add_f32_e32 v2, v2, v4
	v_add_f32_e32 v2, v2, v5
	v_fmamk_f32 v2, v2, 0x3a800000, v250
	v_mul_f32_e32 v3, 0x4b800000, v2
	v_cmp_gt_f32_e64 s[44:45], s4, v2
	s_waitcnt vmcnt(6)
	v_add_u32_e32 v185, v178, v176
	s_waitcnt lgkmcnt(0)
	s_barrier
	v_cndmask_b32_e64 v2, v2, v3, s[44:45]
	v_rsq_f32_e32 v184, v2
	ds_read_b128 v[2:5], v185 offset:15360
	ds_read_b128 v[6:9], v185 offset:14336
	ds_read_b128 v[10:13], v185 offset:13312
	ds_read_b128 v[14:17], v185 offset:12288
	ds_read_b128 v[18:21], v185 offset:11264
	ds_read_b128 v[22:25], v185 offset:10240
	ds_read_b128 v[26:29], v185 offset:9216
	ds_read_b128 v[30:33], v185 offset:8192
	v_add3_u32 v186, s47, v177, v176
	ds_read_b128 v[162:165], v186 offset:3072
	ds_read_b128 v[166:169], v186 offset:2048
	ds_read_b128 v[170:173], v186 offset:1024
	ds_read_b128 v[174:177], v186
	v_rsq_f32_e32 v0, v0
	v_mul_f32_e32 v188, 0x45800000, v182
	v_mul_f32_e32 v189, 0x45800000, v183
	v_mul_f32_e32 v190, 0x45800000, v184
	v_mul_f32_e32 v187, 0x45800000, v0
	s_waitcnt lgkmcnt(0)
	v_mfma_f32_16x16x32_bf16 v[34:37], v[30:33], v[174:177], v[34:37]
	v_mfma_f32_16x16x32_bf16 v[38:41], v[30:33], v[170:173], v[38:41]
	v_mfma_f32_16x16x32_bf16 v[178:181], v[30:33], v[166:169], v[42:45]
	v_mfma_f32_16x16x32_bf16 v[30:33], v[30:33], v[162:165], v[46:49]
	v_mfma_f32_16x16x32_bf16 v[48:51], v[26:29], v[174:177], v[50:53]
	v_mfma_f32_16x16x32_bf16 v[52:55], v[26:29], v[170:173], v[54:57]
	v_mfma_f32_16x16x32_bf16 v[56:59], v[26:29], v[166:169], v[58:61]
	v_mfma_f32_16x16x32_bf16 v[26:29], v[26:29], v[162:165], v[62:65]
	v_mfma_f32_16x16x32_bf16 v[60:63], v[22:25], v[174:177], v[66:69]
	v_mfma_f32_16x16x32_bf16 v[64:67], v[22:25], v[170:173], v[70:73]
	v_mfma_f32_16x16x32_bf16 v[68:71], v[22:25], v[166:169], v[74:77]
	v_mfma_f32_16x16x32_bf16 v[22:25], v[22:25], v[162:165], v[78:81]
	v_mfma_f32_16x16x32_bf16 v[72:75], v[18:21], v[174:177], v[82:85]
	v_mfma_f32_16x16x32_bf16 v[76:79], v[18:21], v[170:173], v[86:89]
	v_mfma_f32_16x16x32_bf16 v[80:83], v[18:21], v[166:169], v[90:93]
	v_mfma_f32_16x16x32_bf16 v[18:21], v[18:21], v[162:165], v[94:97]
	v_mfma_f32_16x16x32_bf16 v[84:87], v[14:17], v[174:177], v[98:101]
	v_mfma_f32_16x16x32_bf16 v[88:91], v[14:17], v[170:173], v[102:105]
	v_mfma_f32_16x16x32_bf16 v[92:95], v[14:17], v[166:169], v[106:109]
	v_mfma_f32_16x16x32_bf16 v[14:17], v[14:17], v[162:165], v[110:113]
	v_mfma_f32_16x16x32_bf16 v[96:99], v[10:13], v[174:177], v[114:117]
	v_mfma_f32_16x16x32_bf16 v[100:103], v[10:13], v[170:173], v[118:121]
	v_mfma_f32_16x16x32_bf16 v[104:107], v[10:13], v[166:169], v[122:125]
	v_mfma_f32_16x16x32_bf16 v[10:13], v[10:13], v[162:165], v[126:129]
	v_mfma_f32_16x16x32_bf16 v[108:111], v[6:9], v[174:177], v[130:133]
	v_mfma_f32_16x16x32_bf16 v[112:115], v[6:9], v[170:173], v[134:137]
	v_mfma_f32_16x16x32_bf16 v[116:119], v[6:9], v[166:169], v[138:141]
	v_mfma_f32_16x16x32_bf16 v[120:123], v[2:5], v[174:177], v[146:149]
	v_mfma_f32_16x16x32_bf16 v[124:127], v[2:5], v[170:173], v[150:153]
	v_mfma_f32_16x16x32_bf16 v[128:131], v[2:5], v[166:169], v[154:157]
	v_mfma_f32_16x16x32_bf16 v[6:9], v[6:9], v[162:165], v[142:145]
	v_mfma_f32_16x16x32_bf16 v[2:5], v[2:5], v[162:165], v[158:161]
	s_waitcnt vmcnt(0)
	v_cndmask_b32_e32 v46, v0, v187, vcc
	v_cndmask_b32_e64 v44, v182, v188, s[40:41]
	v_cndmask_b32_e64 v42, v183, v189, s[42:43]
	v_cndmask_b32_e64 v0, v184, v190, s[44:45]
	s_waitcnt lgkmcnt(0)
	s_barrier
	ds_read_b128 v[132:135], v186 offset:24576
	ds_read_b128 v[136:139], v186 offset:25600
	ds_read_b128 v[140:143], v186 offset:26624
	ds_read_b128 v[144:147], v186 offset:27648
	ds_read_b128 v[148:151], v185 offset:32768
	ds_read_b128 v[152:155], v185 offset:33792
	ds_read_b128 v[156:159], v185 offset:34816
	ds_read_b128 v[160:163], v185 offset:35840
	ds_read_b128 v[164:167], v185 offset:36864
	ds_read_b128 v[168:171], v185 offset:37888
	ds_read_b128 v[172:175], v185 offset:38912
	ds_read_b128 v[182:185], v185 offset:39936
	s_waitcnt lgkmcnt(4)
	v_mfma_f32_16x16x32_bf16 v[242:245], v[160:163], v[140:143], v[80:83]
	v_mfma_f32_16x16x32_bf16 v[246:249], v[160:163], v[144:147], v[18:21]
	s_waitcnt lgkmcnt(3)
	v_mfma_f32_16x16x32_bf16 v[210:213], v[164:167], v[132:135], v[84:87]
	v_mfma_f32_16x16x32_bf16 v[194:197], v[164:167], v[136:139], v[88:91]
	v_mfma_f32_16x16x32_bf16 v[206:209], v[164:167], v[140:143], v[92:95]
	v_mfma_f32_16x16x32_bf16 v[164:167], v[164:167], v[144:147], v[14:17]
	v_mfma_f32_16x16x32_bf16 v[186:189], v[148:151], v[132:135], v[34:37]
	v_mfma_f32_16x16x32_bf16 v[190:193], v[148:151], v[136:139], v[38:41]
	v_mfma_f32_16x16x32_bf16 v[176:179], v[148:151], v[140:143], v[178:181]
	v_mfma_f32_16x16x32_bf16 v[198:201], v[148:151], v[144:147], v[30:33]
	v_mfma_f32_16x16x32_bf16 v[48:51], v[152:155], v[132:135], v[48:51]
	v_mfma_f32_16x16x32_bf16 v[52:55], v[152:155], v[136:139], v[52:55]
	v_mfma_f32_16x16x32_bf16 v[56:59], v[152:155], v[140:143], v[56:59]
	v_mfma_f32_16x16x32_bf16 v[202:205], v[152:155], v[144:147], v[26:29]
	v_mfma_f32_16x16x32_bf16 v[60:63], v[156:159], v[132:135], v[60:63]
	v_mfma_f32_16x16x32_bf16 v[216:219], v[156:159], v[136:139], v[64:67]
	v_mfma_f32_16x16x32_bf16 v[226:229], v[156:159], v[140:143], v[68:71]
	v_mfma_f32_16x16x32_bf16 v[230:233], v[156:159], v[144:147], v[22:25]
	v_mfma_f32_16x16x32_bf16 v[234:237], v[160:163], v[132:135], v[72:75]
	v_mfma_f32_16x16x32_bf16 v[238:241], v[160:163], v[136:139], v[76:79]
	s_waitcnt lgkmcnt(2)
	v_mfma_f32_16x16x32_bf16 v[150:153], v[168:171], v[132:135], v[96:99]
	v_mfma_f32_16x16x32_bf16 v[160:163], v[168:171], v[136:139], v[100:103]
	v_mfma_f32_16x16x32_bf16 v[38:41], v[168:171], v[140:143], v[104:107]
	v_mfma_f32_16x16x32_bf16 v[34:37], v[168:171], v[144:147], v[10:13]
	s_waitcnt lgkmcnt(1)
	v_mfma_f32_16x16x32_bf16 v[30:33], v[172:175], v[132:135], v[108:111]
	v_mfma_f32_16x16x32_bf16 v[26:29], v[172:175], v[136:139], v[112:115]
	v_mfma_f32_16x16x32_bf16 v[22:25], v[172:175], v[140:143], v[116:119]
	v_mfma_f32_16x16x32_bf16 v[18:21], v[172:175], v[144:147], v[6:9]
	s_waitcnt lgkmcnt(0)
	v_mfma_f32_16x16x32_bf16 v[14:17], v[182:185], v[132:135], v[120:123]
	v_mfma_f32_16x16x32_bf16 v[10:13], v[182:185], v[136:139], v[124:127]
	v_mfma_f32_16x16x32_bf16 v[6:9], v[182:185], v[140:143], v[128:131]
	v_mfma_f32_16x16x32_bf16 v[2:5], v[182:185], v[144:147], v[2:5]
	v_mov_b32_e32 v43, v224
	s_lshl_b32 s4, s46, 3
	v_lshrrev_b32_e32 v65, 1, v43
	v_lshlrev_b32_e32 v45, 3, v43
	v_and_b32_e32 v140, 24, v65
	v_ashrrev_i32_e32 v65, 4, v43
	v_and_b32_e32 v47, 56, v45
	v_add_u32_e32 v66, 0x7c, v65
	v_cmp_gt_i32_e32 vcc, 2, v65
	v_ashrrev_i32_e32 v142, 7, v43
	v_and_b32_e32 v64, 0x4f, v43
	v_cmp_gt_i32_e64 s[40:41], 64, v43
	v_cndmask_b32_e32 v66, v66, v65, vcc
	v_and_b32_e32 v67, 0x78, v45
	v_bfe_u32 v45, v45, 6, 1
	v_lshl_add_u32 v65, v65, 1, s4
	v_ashrrev_i32_e32 v43, 3, v43
	s_movk_i32 s4, 0xffe1
	v_pk_mul_f32 v[48:49], v[46:47], v[48:49] op_sel_hi:[0,1]
	v_or_b32_e32 v45, v65, v45
	v_cmp_lt_i32_e64 s[44:45], s4, v43
	s_movk_i32 s4, 0xffc1
	v_cvt_pk_bf16_f32 v74, v48, v49
	v_pk_mul_f32 v[48:49], v[46:47], v[50:51] op_sel_hi:[0,1]
	s_movk_i32 s5, 0x110
	v_add_u32_e32 v132, s15, v43
	v_cmp_lt_i32_e64 s[46:47], s4, v43
	s_movk_i32 s4, 0xffa1
	v_cvt_pk_bf16_f32 v75, v48, v49
	v_pk_mul_f32 v[48:49], v[44:45], v[52:53] op_sel_hi:[0,1]
	v_mul_u32_u24_e32 v141, 0x110, v64
	v_cmp_lt_i32_e64 s[42:43], 1, v43
	v_mul_lo_u32 v64, v43, s5
	v_cmp_lt_i32_e64 s[48:49], s4, v43
	v_add_u32_e32 v43, 0x60, v132
	v_cvt_pk_bf16_f32 v76, v48, v49
	v_pk_mul_f32 v[48:49], v[44:45], v[54:55] op_sel_hi:[0,1]
	v_cvt_pk_bf16_f32 v77, v48, v49
	v_pk_mul_f32 v[48:49], v[42:43], v[56:57] op_sel_hi:[0,1]
	v_cvt_pk_bf16_f32 v78, v48, v49
	v_pk_mul_f32 v[48:49], v[42:43], v[58:59] op_sel_hi:[0,1]
	v_cvt_pk_bf16_f32 v79, v48, v49
	v_pk_mul_f32 v[48:49], v[0:1], v[202:203] op_sel_hi:[0,1]
	v_cvt_pk_bf16_f32 v80, v48, v49
	v_pk_mul_f32 v[48:49], v[0:1], v[204:205] op_sel_hi:[0,1]
	v_cvt_pk_bf16_f32 v81, v48, v49
	v_pk_mul_f32 v[48:49], v[46:47], v[60:61] op_sel_hi:[0,1]
	v_cvt_pk_bf16_f32 v82, v48, v49
	v_pk_mul_f32 v[48:49], v[46:47], v[62:63] op_sel_hi:[0,1]
	v_cvt_pk_bf16_f32 v83, v48, v49
	v_pk_mul_f32 v[48:49], v[44:45], v[216:217] op_sel_hi:[0,1]
	v_cvt_pk_bf16_f32 v84, v48, v49
	v_pk_mul_f32 v[48:49], v[44:45], v[218:219] op_sel_hi:[0,1]
	v_cvt_pk_bf16_f32 v85, v48, v49
	v_pk_mul_f32 v[48:49], v[42:43], v[226:227] op_sel_hi:[0,1]
	v_cvt_pk_bf16_f32 v86, v48, v49
	v_pk_mul_f32 v[48:49], v[42:43], v[228:229] op_sel_hi:[0,1]
	v_cvt_pk_bf16_f32 v87, v48, v49
	v_pk_mul_f32 v[48:49], v[0:1], v[230:231] op_sel_hi:[0,1]
	v_cvt_pk_bf16_f32 v88, v48, v49
	v_pk_mul_f32 v[48:49], v[0:1], v[232:233] op_sel_hi:[0,1]
	v_cvt_pk_bf16_f32 v89, v48, v49
	v_pk_mul_f32 v[48:49], v[46:47], v[234:235] op_sel_hi:[0,1]
	v_cvt_pk_bf16_f32 v90, v48, v49
	v_pk_mul_f32 v[48:49], v[46:47], v[236:237] op_sel_hi:[0,1]
	v_cvt_pk_bf16_f32 v91, v48, v49
	v_pk_mul_f32 v[48:49], v[44:45], v[238:239] op_sel_hi:[0,1]
	v_cvt_pk_bf16_f32 v92, v48, v49
	v_pk_mul_f32 v[48:49], v[44:45], v[240:241] op_sel_hi:[0,1]
	v_cvt_pk_bf16_f32 v93, v48, v49
	v_pk_mul_f32 v[48:49], v[42:43], v[242:243] op_sel_hi:[0,1]
	v_cvt_pk_bf16_f32 v94, v48, v49
	v_pk_mul_f32 v[48:49], v[42:43], v[244:245] op_sel_hi:[0,1]
	v_cvt_pk_bf16_f32 v95, v48, v49
	v_pk_mul_f32 v[48:49], v[0:1], v[246:247] op_sel_hi:[0,1]
	v_cvt_pk_bf16_f32 v96, v48, v49
	v_pk_mul_f32 v[48:49], v[0:1], v[248:249] op_sel_hi:[0,1]
	v_cvt_pk_bf16_f32 v97, v48, v49
	v_pk_mul_f32 v[48:49], v[46:47], v[210:211] op_sel_hi:[0,1]
	v_cvt_pk_bf16_f32 v98, v48, v49
	v_pk_mul_f32 v[48:49], v[46:47], v[212:213] op_sel_hi:[0,1]
	v_cvt_pk_bf16_f32 v99, v48, v49
	v_pk_mul_f32 v[48:49], v[44:45], v[194:195] op_sel_hi:[0,1]
	v_cvt_pk_bf16_f32 v100, v48, v49
	v_pk_mul_f32 v[48:49], v[44:45], v[196:197] op_sel_hi:[0,1]
	v_mul_lo_u32 v66, v66, s5
	v_lshl_add_u32 v144, v47, 1, v64
	v_pk_mul_f32 v[64:65], v[46:47], v[186:187] op_sel_hi:[0,1]
	v_cvt_pk_bf16_f32 v101, v48, v49
	v_pk_mul_f32 v[48:49], v[42:43], v[206:207] op_sel_hi:[0,1]
	v_lshl_add_u32 v143, v67, 1, v66
	v_cvt_pk_bf16_f32 v66, v64, v65
	v_pk_mul_f32 v[64:65], v[46:47], v[188:189] op_sel_hi:[0,1]
	v_cvt_pk_bf16_f32 v102, v48, v49
	v_pk_mul_f32 v[48:49], v[42:43], v[208:209] op_sel_hi:[0,1]
	v_cvt_pk_bf16_f32 v67, v64, v65
	v_pk_mul_f32 v[64:65], v[44:45], v[190:191] op_sel_hi:[0,1]
	v_cvt_pk_bf16_f32 v103, v48, v49
	v_pk_mul_f32 v[48:49], v[0:1], v[164:165] op_sel_hi:[0,1]
	v_cvt_pk_bf16_f32 v68, v64, v65
	v_pk_mul_f32 v[64:65], v[44:45], v[192:193] op_sel_hi:[0,1]
	v_cvt_pk_bf16_f32 v104, v48, v49
	v_pk_mul_f32 v[48:49], v[0:1], v[166:167] op_sel_hi:[0,1]
	v_pk_mul_f32 v[2:3], v[0:1], v[2:3] op_sel_hi:[0,1]
	v_cvt_pk_bf16_f32 v69, v64, v65
	v_pk_mul_f32 v[64:65], v[42:43], v[176:177] op_sel_hi:[0,1]
	v_cvt_pk_bf16_f32 v105, v48, v49
	v_pk_mul_f32 v[48:49], v[46:47], v[150:151] op_sel_hi:[0,1]
	v_cvt_pk_bf16_f32 v128, v2, v3
	v_pk_mul_f32 v[2:3], v[0:1], v[4:5] op_sel_hi:[0,1]
	v_cvt_pk_bf16_f32 v70, v64, v65
	v_pk_mul_f32 v[64:65], v[42:43], v[178:179] op_sel_hi:[0,1]
	v_cvt_pk_bf16_f32 v106, v48, v49
	v_pk_mul_f32 v[48:49], v[46:47], v[152:153] op_sel_hi:[0,1]
	v_cvt_pk_bf16_f32 v129, v2, v3
	v_mov_b64_e32 v[2:3], s[54:55]
	v_add_u32_e32 v134, 32, v132
	v_add_u32_e32 v136, 64, v132
	v_cvt_pk_bf16_f32 v71, v64, v65
	v_pk_mul_f32 v[64:65], v[0:1], v[198:199] op_sel_hi:[0,1]
	v_cvt_pk_bf16_f32 v107, v48, v49
	v_pk_mul_f32 v[48:49], v[44:45], v[160:161] op_sel_hi:[0,1]
	v_pk_mul_f32 v[38:39], v[42:43], v[38:39] op_sel_hi:[0,1]
	v_pk_mul_f32 v[34:35], v[0:1], v[34:35] op_sel_hi:[0,1]
	v_pk_mul_f32 v[30:31], v[46:47], v[30:31] op_sel_hi:[0,1]
	v_pk_mul_f32 v[26:27], v[44:45], v[26:27] op_sel_hi:[0,1]
	v_pk_mul_f32 v[22:23], v[42:43], v[22:23] op_sel_hi:[0,1]
	v_pk_mul_f32 v[18:19], v[0:1], v[18:19] op_sel_hi:[0,1]
	v_pk_mul_f32 v[14:15], v[46:47], v[14:15] op_sel_hi:[0,1]
	v_pk_mul_f32 v[10:11], v[44:45], v[10:11] op_sel_hi:[0,1]
	v_pk_mul_f32 v[6:7], v[42:43], v[6:7] op_sel_hi:[0,1]
	v_mad_i64_i32 v[130:131], s[4:5], v45, s19, v[2:3]
	v_mov_b64_e32 v[2:3], s[52:53]
	v_cvt_pk_bf16_f32 v72, v64, v65
	v_pk_mul_f32 v[64:65], v[0:1], v[200:201] op_sel_hi:[0,1]
	v_cvt_pk_bf16_f32 v108, v48, v49
	v_pk_mul_f32 v[48:49], v[44:45], v[162:163] op_sel_hi:[0,1]
	v_cvt_pk_bf16_f32 v110, v38, v39
	v_pk_mul_f32 v[38:39], v[42:43], v[40:41] op_sel_hi:[0,1]
	v_cvt_pk_bf16_f32 v112, v34, v35
	v_pk_mul_f32 v[34:35], v[0:1], v[36:37] op_sel_hi:[0,1]
	v_cvt_pk_bf16_f32 v114, v30, v31
	v_pk_mul_f32 v[30:31], v[46:47], v[32:33] op_sel_hi:[0,1]
	v_cvt_pk_bf16_f32 v116, v26, v27
	v_pk_mul_f32 v[26:27], v[44:45], v[28:29] op_sel_hi:[0,1]
	v_cvt_pk_bf16_f32 v118, v22, v23
	v_pk_mul_f32 v[22:23], v[42:43], v[24:25] op_sel_hi:[0,1]
	v_cvt_pk_bf16_f32 v120, v18, v19
	v_pk_mul_f32 v[18:19], v[0:1], v[20:21] op_sel_hi:[0,1]
	v_cvt_pk_bf16_f32 v122, v14, v15
	v_pk_mul_f32 v[14:15], v[46:47], v[16:17] op_sel_hi:[0,1]
	v_cvt_pk_bf16_f32 v124, v10, v11
	v_pk_mul_f32 v[10:11], v[44:45], v[12:13] op_sel_hi:[0,1]
	v_cvt_pk_bf16_f32 v126, v6, v7
	v_pk_mul_f32 v[6:7], v[42:43], v[8:9] op_sel_hi:[0,1]
	v_mad_i64_i32 v[132:133], s[4:5], v132, s19, v[2:3]
	v_mad_i64_i32 v[134:135], s[4:5], v134, s19, v[2:3]
	v_mad_i64_i32 v[136:137], s[4:5], v136, s19, v[2:3]
	v_mad_i64_i32 v[138:139], s[4:5], v43, s19, v[2:3]
	v_add_u32_e32 v145, 0xfffffef0, v144
	v_add_u32_e32 v146, 0xffffff70, v144
	v_add_u32_e32 v147, 0xfffffde0, v144
	v_add_u32_e32 v148, 0xfffffe60, v144
	v_add_u32_e32 v149, 0x2200, v144
	v_add_u32_e32 v168, 0x20f0, v144
	v_add_u32_e32 v169, 0x2170, v144
	v_add_u32_e32 v170, 0x1fe0, v144
	v_add_u32_e32 v171, 0x2060, v144
	v_add_u32_e32 v154, 0x4400, v144
	v_add_u32_e32 v155, 0x42f0, v144
	v_add_u32_e32 v156, 0x4370, v144
	v_add_u32_e32 v157, 0x41e0, v144
	v_add_u32_e32 v158, 0x4260, v144
	v_add_u32_e32 v159, 0x6600, v144
	v_add_u32_e32 v172, 0x64f0, v144
	v_add_u32_e32 v173, 0x6570, v144
	v_add_u32_e32 v174, 0x63e0, v144
	v_add_u32_e32 v175, 0x6460, v144
	v_cvt_pk_bf16_f32 v73, v64, v65
	v_cvt_pk_bf16_f32 v109, v48, v49
	v_cvt_pk_bf16_f32 v111, v38, v39
	v_cvt_pk_bf16_f32 v113, v34, v35
	v_cvt_pk_bf16_f32 v115, v30, v31
	v_cvt_pk_bf16_f32 v117, v26, v27
	v_cvt_pk_bf16_f32 v119, v22, v23
	v_cvt_pk_bf16_f32 v121, v18, v19
	v_cvt_pk_bf16_f32 v123, v14, v15
	v_cvt_pk_bf16_f32 v125, v10, v11
	v_cvt_pk_bf16_f32 v127, v6, v7
	v_lshl_or_b32 v0, s14, 7, v47
	s_mov_b32 s4, 0
	s_mov_b64 s[12:13], -1
	v_add_u32_e32 v164, v140, v141
	v_xor_b32_e32 v246, 32, v225
	v_xor_b32_e32 v247, 16, v225
	v_xor_b32_e32 v248, 8, v225
	v_xor_b32_e32 v249, 4, v225
	v_mov_b32_e32 v243, v221
	s_branch .LBB0_171

.LBB0_658:
	v_add_u32_e32 v0, s14, v14
	v_cndmask_b32_e64 v0, v0, v15, s[44:45]
	s_waitcnt lgkmcnt(3)
	v_cvt_pk_bf16_f32 v4, v4, v5
	s_waitcnt lgkmcnt(2)
	v_cvt_pk_bf16_f32 v5, v6, v7
	s_waitcnt lgkmcnt(1)
	v_cvt_pk_bf16_f32 v6, v8, v9
	v_mad_i64_i32 v[8:9], s[12:13], v0, s100, 0
	s_waitcnt lgkmcnt(0)
	v_cvt_pk_bf16_f32 v7, v10, v11
	v_lshl_add_u64 v[2:3], v[8:9], 1, v[2:3]
	global_store_dwordx4 v[2:3], v[4:7], off

.LBB0_702:
	s_or_b64 exec, exec, s[14:15]
	s_waitcnt lgkmcnt(0)
	s_add_u32 s69, s86, s46
	s_addc_u32 s79, s87, s47
	s_movk_i32 s14, 0x104
	s_cmp_gt_i32 s53, -1
	s_mov_b32 s94, s53
	v_mul_lo_u32 v0, v37, s14
	s_cselect_b64 s[46:47], -1, 0
	s_lshl_b64 s[14:15], s[94:95], 3
	v_readlane_b32 s44, v253, 0
	v_readlane_b32 s45, v253, 1
	s_add_u32 s70, s44, s14
	s_addc_u32 s71, s45, s15
	s_ashr_i32 s55, s54, 31
	s_ashr_i32 s49, s48, 31
	v_lshl_add_u32 v0, v36, 2, v0
	s_cmp_eq_u32 s52, 0
	s_waitcnt vmcnt(0)
	ds_write2_b32 v0, v6, v7 offset1:1
	ds_write2_b32 v0, v8, v9 offset0:2 offset1:3
	v_add_u32_e32 v6, 0x1040, v0
	s_cselect_b64 s[44:45], -1, 0
	s_add_i32 s14, s68, 0xfffff540
	ds_write2_b32 v6, v2, v3 offset1:1
	v_add_u32_e32 v2, 0x1048, v0
	s_lshr_b32 s14, s14, 6
	ds_write2_b32 v2, v4, v5 offset1:1
	v_add_u32_e32 v2, 0x2080, v0
	s_cmp_gt_i32 s78, 42
	ds_write2_b32 v2, v14, v15 offset1:1
	v_add_u32_e32 v2, 0x2088, v0
	s_cselect_b32 s14, s14, s78
	ds_write2_b32 v2, v16, v17 offset1:1
	v_add_u32_e32 v2, 0x30c0, v0
	v_add_u32_e32 v0, 0x30c8, v0
	s_cselect_b32 s15, 64, 0
	s_lshl_b32 s14, s14, 7
	ds_write2_b32 v0, v12, v13 offset1:1
	v_lshlrev_b32_e32 v0, 3, v35
	s_or_b32 s14, s14, s15
	s_lshl_b64 s[52:53], s[48:49], 1
	v_ashrrev_i32_e32 v13, 3, v35
	v_and_b32_e32 v12, 56, v0
	s_add_u32 s52, s69, s52
	s_addc_u32 s53, s79, s53
	v_lshlrev_b32_e32 v0, 1, v12
	v_add_u32_e32 v14, s68, v13
	v_cndmask_b32_e64 v4, 0, 1, s[46:47]
	ds_write2_b32 v2, v10, v11 offset1:1
	v_lshl_add_u64 v[2:3], s[52:53], 0, v[0:1]
	s_mov_b32 s100, s12
	s_cmp_eq_u32 s94, 2
	s_cbranch_scc0 .Lmy_kb_skip
	s_movk_i32 s100, 32
	s_lshr_b32 s101, s48, 5
	s_mul_i32 s101, s101, s13
	s_lshl_b32 s101, s101, 6
	s_add_u32 vcc_lo, s69, s101
	s_addc_u32 vcc_hi, s79, 0
	s_lshl_b32 s101, s13, 6
	v_lshrrev_b32_e32 v212, 5, v12
	v_mul_lo_u32 v212, v212, s101
	v_and_b32_e32 v213, 31, v12
	v_lshl_add_u32 v212, v213, 1, v212
	v_mov_b32_e32 v213, 0
	v_lshl_add_u64 v[2:3], vcc, 0, v[212:213]
.Lmy_kb_skip:
	v_cmp_gt_i32_e32 vcc, s13, v14
	v_mul_u32_u24_e32 v0, 0x104, v12
	v_cmp_ne_u32_e64 s[46:47], 1, v4
	s_waitcnt lgkmcnt(0)
	s_barrier
	s_and_saveexec_b64 s[52:53], vcc
	s_cbranch_execz .LBB0_706
	v_lshl_add_u32 v8, v13, 2, v0
	v_add_u32_e32 v10, 0x400, v8
	ds_read2_b32 v[4:5], v8 offset1:65
	ds_read2_b32 v[6:7], v8 offset0:130 offset1:195
	ds_read2_b32 v[8:9], v10 offset0:4 offset1:69
	ds_read2_b32 v[10:11], v10 offset0:134 offset1:199
	s_and_b64 vcc, exec, s[46:47]
	s_cbranch_vccnz .LBB0_705
	s_load_dwordx2 s[78:79], s[70:71], 0x0
	s_lshl_b64 s[80:81], s[54:55], 2
	v_lshlrev_b32_e32 v15, 2, v12
	s_waitcnt lgkmcnt(0)
	s_add_u32 s15, s78, s80
	s_addc_u32 s69, s79, s81
	v_readlane_b32 s78, v254, 44
	v_readlane_b32 s79, v254, 45
	s_add_u32 s15, s15, s78
	s_addc_u32 s69, s69, s79
	s_lshl_b64 s[78:79], s[48:49], 2
	s_add_u32 s78, s15, s78
	s_addc_u32 s79, s69, s79
	global_load_dwordx4 v[36:39], v15, s[78:79]
	global_load_dwordx4 v[40:43], v15, s[78:79] offset:16
	s_movk_i32 s80, 0x3000
	s_movk_i32 s81, 0x2000
	s_waitcnt vmcnt(1)
	v_pk_mul_f32 v[4:5], v[4:5], v[36:37]
	v_pk_mul_f32 v[6:7], v[6:7], v[38:39]
	s_waitcnt vmcnt(0)
	v_pk_mul_f32 v[8:9], v[8:9], v[40:41]
	v_pk_mul_f32 v[10:11], v[10:11], v[42:43]
	s_cmpk_lt_u32 s68, 0x400
	s_cbranch_scc0 .Lmy_nosc_b
	s_cmp_eq_u32 s94, 9
	s_cbranch_scc1 .Lmy_dosc_b
	s_cmp_eq_u32 s94, 1
	s_cbranch_scc0 .Lmy_nosc_b
	s_cmpk_lt_u32 s54, 0x800
	s_cbranch_scc0 .Lmy_nosc_b

.Lmy_nosc_b:
.LBB0_705:
	v_add_u32_e32 v15, s14, v13
	v_cndmask_b32_e64 v14, v15, v14, s[44:45]
	s_waitcnt lgkmcnt(3)
	v_cvt_pk_bf16_f32 v4, v4, v5
	s_waitcnt lgkmcnt(2)
	v_cvt_pk_bf16_f32 v5, v6, v7
	s_waitcnt lgkmcnt(1)
	v_cvt_pk_bf16_f32 v6, v8, v9
	v_mad_i64_i32 v[8:9], s[78:79], v14, s100, 0
	s_waitcnt lgkmcnt(0)
	v_cvt_pk_bf16_f32 v7, v10, v11
	v_lshl_add_u64 v[8:9], v[8:9], 1, v[2:3]
	global_store_dwordx4 v[8:9], v[4:7], off
